# conv loop do0/do1 wave-uniform branch tests made pure scalar (s_andn2 + s_cbranch_scc1), VALU cndmask/cmp chain removed
# speedup vs baseline: 1.0003x; 1.0003x over previous
; __device__ __forceinline__ void hyena_conv_mfma(const Args& a, int l, int o, unsigned char* sm, const bf16_t* __restrict__ FILT, const u64_t* __restrict__ FSUM,
;                                                 const bf16_t* __restrict__ ZinT, const bf16_t* __restrict__ GT, bf16_t* __restrict__ OutT) {
;     ...
;         for (int it = 0; it < 64; ++it) {
;             const bool do0 = !(wks == 1 && it >= 51), do1 = !(wks == 0 && it < 12);
; #pragma unroll
;             for (int u = 0; u < 5; ++u) {
;                 const int j = it * 5 + u;
;                 { u32x4 oa, ob;
;                   oa.x = __builtin_amdgcn_alignbit(ra[1], ra[0], sh); oa.y = __builtin_amdgcn_alignbit(ra[2], ra[1], sh); oa.z = __builtin_amdgcn_alignbit(ra[3], ra[2], sh); oa.w = __builtin_amdgcn_alignbit(ra[4], ra[3], sh);
;                   ob.x = __builtin_amdgcn_alignbit(rb[1], rb[0], sh); ob.y = __builtin_amdgcn_alignbit(rb[2], rb[1], sh); ob.z = __builtin_amdgcn_alignbit(rb[3], rb[2], sh); ob.w = __builtin_amdgcn_alignbit(rb[4], rb[3], sh);
;                   R[(2 * u + 6) % 10] = __builtin_bit_cast(bf16x8, oa); R[(2 * u + 7) % 10] = __builtin_bit_cast(bf16x8, ob); }
;                 const bf16x8 zb0 = zr0, zb1 = zr1;
;                 { const int dwa = (xb + 16 * (2 * j + 8)) >> 1, dwb = (xb + 16 * (2 * j + 9)) >> 1;
; #pragma unroll
;                   for (int e = 0; e < 5; ++e) { ra[e] = kd[dwa + e]; rb[e] = kd[dwb + e]; } }
;                 zr0 = *(const bf16x8*)(zp + zpad(zi0 + 32 * (j + 1))); zr1 = *(const bf16x8*)(zp + zpad(zi0 + 32 * (j + 1) - 16 * 128));
;                 __builtin_amdgcn_sched_barrier(0);
;                 if (do0) {
; #pragma unroll
;                     for (int q = 0; q < 8; ++q) acc[q][0] = __builtin_amdgcn_mfma_f32_16x16x32_bf16(R[(2 * u + q) % 10], zb0, acc[q][0], 0, 0, 0);
;                 }
;                 if (do1) {
; #pragma unroll
;                     for (int q = 0; q < 8; ++q) acc[q][1] = __builtin_amdgcn_mfma_f32_16x16x32_bf16(R[(2 * u + q) % 10], zb1, acc[q][1], 0, 0, 0);
;                 }
.LBB0_409:
	s_waitcnt lgkmcnt(8)
	ds_read2_b32 v[102:103], v201 offset1:1
	ds_read2_b32 v[108:109], v201 offset0:1 offset1:2
	ds_read2_b32 v[106:107], v201 offset0:8 offset1:9
	ds_read2_b32 v[126:127], v201 offset0:9 offset1:10
	ds_read2_b32 v[104:105], v201 offset0:3 offset1:4
	ds_read2_b32 v[128:129], v201 offset0:11 offset1:12
	s_add_i32 s100, s2, 0x820
	s_lshr_b32 s100, s100, 7
	s_lshl_b32 s100, s100, 4
	v_add_u32_e32 v118, s100, v185
	s_waitcnt lgkmcnt(11)
	v_alignbit_b32 v94, v96, v94, v0
	v_alignbit_b32 v95, v97, v96, v0
	s_waitcnt lgkmcnt(9)
	v_alignbit_b32 v96, v98, v97, v0
	v_alignbit_b32 v97, v99, v98, v0
	s_waitcnt lgkmcnt(9)
	v_alignbit_b32 v98, v100, v124, v0
	v_alignbit_b32 v99, v101, v100, v0
	s_waitcnt lgkmcnt(8)
	v_alignbit_b32 v100, v122, v101, v0
	v_alignbit_b32 v101, v123, v122, v0
	ds_read_b128 v[122:125], v118 offset:4352
	ds_read_b128 v[118:121], v118
	s_cmp_lt_u32 s3, 51
	s_cselect_b64 s[26:27], -1, 0
	s_or_b64 s[28:29], s[56:57], s[26:27]
	s_andn2_b64 s[26:27], exec, s[28:29]
	s_cbranch_scc1 .LBB0_411
	s_waitcnt lgkmcnt(9)
	v_mfma_f32_16x16x32_bf16 v[66:69], v[70:73], v[114:117], v[66:69]
	v_mfma_f32_16x16x32_bf16 v[56:59], v[74:77], v[114:117], v[56:59]
	v_mfma_f32_16x16x32_bf16 v[48:51], v[78:81], v[114:117], v[48:51]
	v_mfma_f32_16x16x32_bf16 v[40:43], v[82:85], v[114:117], v[40:43]
	v_mfma_f32_16x16x32_bf16 v[32:35], v[86:89], v[114:117], v[32:35]
	v_mfma_f32_16x16x32_bf16 v[24:27], v[90:93], v[114:117], v[24:27]
	v_mfma_f32_16x16x32_bf16 v[16:19], v[94:97], v[114:117], v[16:19]
	v_mfma_f32_16x16x32_bf16 v[8:11], v[98:101], v[114:117], v[8:11]
.LBB0_411:
	s_cmp_gt_u32 s3, 11
	s_cselect_b64 s[28:29], -1, 0
	s_or_b64 vcc, s[58:59], s[28:29]
	s_waitcnt lgkmcnt(9)
	s_andn2_b64 s[28:29], exec, vcc
	s_cbranch_scc1 .LBB0_413
	s_waitcnt lgkmcnt(8)
	v_mfma_f32_16x16x32_bf16 v[60:63], v[70:73], v[110:113], v[60:63]
	v_mfma_f32_16x16x32_bf16 v[52:55], v[74:77], v[110:113], v[52:55]
	v_mfma_f32_16x16x32_bf16 v[44:47], v[78:81], v[110:113], v[44:47]
	v_mfma_f32_16x16x32_bf16 v[36:39], v[82:85], v[110:113], v[36:39]
	v_mfma_f32_16x16x32_bf16 v[28:31], v[86:89], v[110:113], v[28:31]
	v_mfma_f32_16x16x32_bf16 v[20:23], v[90:93], v[110:113], v[20:23]
	v_mfma_f32_16x16x32_bf16 v[12:15], v[94:97], v[110:113], v[12:15]
	v_mfma_f32_16x16x32_bf16 v[4:7], v[98:101], v[110:113], v[4:7]
